# attention loops: K-fragment LDS reads ordered first-score-half first, one lgkmcnt(0) replaced by counted waits before each QK MFMA
# speedup vs baseline: 1.0051x; 1.0023x over previous
.LBB0_87:
	s_add_i32 s20, s22, 1
	s_movk_i32 s21, 0x5000
	s_cmp_gt_i32 s22, s78
	s_cbranch_scc1 .LmlaE_skipdma
	ds_read_b128 v[32:35], v168
	ds_read_b128 v[40:43], v170
	ds_read_b128 v[44:47], v172
	ds_read_b128 v[88:91], v174
	ds_read_b128 v[92:95], v176
	ds_read_b128 v[96:99], v244
	ds_read_b128 v[36:39], v168 offset:6144
	ds_read_b128 v[148:151], v170 offset:6144
	ds_read_b128 v[152:155], v172 offset:6144
	ds_read_b128 v[156:159], v174 offset:6144
	ds_read_b128 v[208:211], v176 offset:6144
	ds_read_b128 v[212:215], v244 offset:6144
	s_add_u32 m0, s21, s32
	s_add_u32 s18, s21, s73
	global_load_lds_dwordx4 v120, s[36:37]
	s_add_u32 m0, m0, 0x400
	s_nop 0
	global_load_lds_dwordx4 v122, s[36:37]
	s_add_u32 m0, m0, 0x400
	s_nop 0
	global_load_lds_dwordx4 v124, s[36:37]
	s_add_u32 m0, s18, 0x3000
	s_nop 0
	global_load_lds_dwordx4 v116, s[38:39]
	s_add_u32 m0, s18, 0x3400
	s_nop 0
	global_load_lds_dwordx4 v118, s[38:39]
	s_waitcnt lgkmcnt(11)
	v_mfma_f32_32x32x16_bf16 v[48:63], v[32:35], v[84:87], v[228:243]
	ds_read_b128 v[216:219], v245 offset:12288
	ds_read_b128 v[108:111], v246 offset:12288
	s_waitcnt lgkmcnt(12)
	v_mfma_f32_32x32x16_bf16 v[48:63], v[40:43], v[80:83], v[48:63]
	s_waitcnt lgkmcnt(11)
	v_mfma_f32_32x32x16_bf16 v[48:63], v[44:47], v[76:79], v[48:63]
	s_waitcnt lgkmcnt(10)
	v_mfma_f32_32x32x16_bf16 v[48:63], v[88:91], v[72:75], v[48:63]
	ds_read_b128 v[88:91], v247 offset:12288
	s_waitcnt lgkmcnt(10)
	v_mfma_f32_32x32x16_bf16 v[48:63], v[92:95], v[68:71], v[48:63]
	s_waitcnt lgkmcnt(9)
	v_mfma_f32_32x32x16_bf16 v[48:63], v[96:99], v[64:67], v[48:63]
	ds_read_b128 v[92:95], v248 offset:12288
	ds_read_b128 v[220:223], v245 offset:16384
	ds_read_b128 v[104:107], v246 offset:16384
	ds_read_b128 v[100:103], v247 offset:16384
	ds_read_b128 v[96:99], v248 offset:16384
	s_nop 6
	s_nop 0
	v_exp_f32_e32 v32, v62
	v_exp_f32_e32 v33, v63
	s_nop 0
	v_add_f32_e32 v224, 0, v32
	v_add_f32_e32 v225, 0, v33
	v_cvt_pk_bf16_f32 v63, v32, v33
	s_waitcnt lgkmcnt(13)
	v_mfma_f32_32x32x16_bf16 v[32:47], v[36:39], v[84:87], v[228:243]
	s_waitcnt lgkmcnt(12)
	v_mfma_f32_32x32x16_bf16 v[32:47], v[148:151], v[80:83], v[32:47]
	v_exp_f32_e32 v60, v60
	v_exp_f32_e32 v61, v61
	s_nop 0
	v_add_f32_e32 v224, v60, v224
	v_add_f32_e32 v225, v61, v225
	v_cvt_pk_bf16_f32 v62, v60, v61
	v_exp_f32_e32 v58, v58
	v_exp_f32_e32 v59, v59
	v_exp_f32_e32 v56, v56
	v_exp_f32_e32 v57, v57
	s_waitcnt lgkmcnt(11)
	v_mfma_f32_32x32x16_bf16 v[32:47], v[152:155], v[76:79], v[32:47]
	v_add_f32_e64 v148, v58, v224
	v_add_f32_e64 v149, v59, v225
	v_cvt_pk_bf16_f32 v61, v58, v59
	v_add_f32_e64 v58, v56, v148
	v_add_f32_e64 v59, v57, v149
	v_cvt_pk_bf16_f32 v60, v56, v57
	s_waitcnt lgkmcnt(10)
	v_mfma_f32_32x32x16_bf16 v[32:47], v[156:159], v[72:75], v[32:47]
	v_exp_f32_e32 v54, v54
	v_exp_f32_e32 v55, v55
	s_nop 0
	v_add_f32_e32 v56, v54, v58
	v_add_f32_e32 v57, v55, v59
	v_cvt_pk_bf16_f32 v55, v54, v55
	s_waitcnt lgkmcnt(9)
	v_mfma_f32_32x32x16_bf16 v[32:47], v[208:211], v[68:71], v[32:47]
	v_exp_f32_e32 v52, v52
	v_exp_f32_e32 v53, v53
	s_nop 0
	v_add_f32_e32 v56, v52, v56
	v_add_f32_e32 v57, v53, v57
	v_cvt_pk_bf16_f32 v54, v52, v53
	v_exp_f32_e32 v50, v50
	v_exp_f32_e32 v51, v51
	v_exp_f32_e32 v48, v48
	v_exp_f32_e32 v49, v49
	s_waitcnt lgkmcnt(8)
	v_mfma_f32_32x32x16_bf16 v[32:47], v[212:215], v[64:67], v[32:47]
	v_add_f32_e64 v56, v50, v56
	v_add_f32_e64 v57, v51, v57
	v_cvt_pk_bf16_f32 v53, v50, v51
	v_cvt_pk_bf16_f32 v52, v48, v49
	v_add_f32_e64 v48, v48, v56
	v_add_f32_e64 v49, v49, v57
	s_waitcnt lgkmcnt(0)
	v_mfma_f32_32x32x16_bf16 v[0:15], v[216:219], v[52:55], v[0:15]
	s_nop 3
	v_exp_f32_e32 v46, v46
	v_exp_f32_e32 v47, v47
	v_exp_f32_e32 v44, v44
	v_exp_f32_e32 v45, v45
	v_add_f32_e32 v48, v48, v46
	v_add_f32_e32 v49, v49, v47
	v_cvt_pk_bf16_f32 v47, v46, v47
	v_add_f32_e32 v48, v44, v48
	v_add_f32_e32 v49, v45, v49
	v_cvt_pk_bf16_f32 v46, v44, v45
	v_mfma_f32_32x32x16_bf16 v[16:31], v[220:223], v[52:55], v[16:31]
	v_exp_f32_e32 v42, v42
	v_exp_f32_e32 v43, v43
	v_exp_f32_e32 v40, v40
	v_exp_f32_e32 v41, v41
	v_add_f32_e32 v48, v42, v48
	v_add_f32_e32 v49, v43, v49
	v_cvt_pk_bf16_f32 v45, v42, v43
	v_add_f32_e32 v42, v40, v48
	v_add_f32_e32 v43, v41, v49
	v_cvt_pk_bf16_f32 v44, v40, v41
	v_mfma_f32_32x32x16_bf16 v[0:15], v[108:111], v[60:63], v[0:15]
	v_exp_f32_e32 v38, v38
	v_exp_f32_e32 v39, v39
	v_exp_f32_e32 v36, v36
	v_exp_f32_e32 v37, v37
	v_add_f32_e32 v40, v38, v42
	v_add_f32_e32 v41, v39, v43
	v_cvt_pk_bf16_f32 v39, v38, v39
	v_add_f32_e32 v40, v36, v40
	v_add_f32_e32 v41, v37, v41
	v_cvt_pk_bf16_f32 v38, v36, v37
	v_mfma_f32_32x32x16_bf16 v[16:31], v[104:107], v[60:63], v[16:31]
	v_exp_f32_e32 v34, v34
	v_exp_f32_e32 v35, v35
	v_exp_f32_e32 v32, v32
	v_exp_f32_e32 v33, v33
	v_cvt_pk_bf16_f32 v37, v34, v35
	v_cvt_pk_bf16_f32 v36, v32, v33
	s_nop 1
	v_mfma_f32_32x32x16_bf16 v[0:15], v[88:91], v[36:39], v[0:15]
	v_add_f32_e64 v34, v34, v40
	v_add_f32_e64 v35, v35, v41
	v_add_f32_e64 v32, v32, v34
	v_add_f32_e64 v33, v33, v35
	v_add_f32_e32 v32, v32, v33
	v_add_f32_e32 v126, v126, v32
	v_mfma_f32_32x32x16_bf16 v[16:31], v[100:103], v[36:39], v[16:31]
	v_mfma_f32_32x32x16_bf16 v[0:15], v[92:95], v[44:47], v[0:15]
	v_mfma_f32_32x32x16_bf16 v[16:31], v[96:99], v[44:47], v[16:31]
	s_branch .Lmla_o86

.Lmla_o87:
	s_add_i32 s20, s22, 1
	s_mov_b32 s21, 0
	s_cmp_gt_i32 s22, s78
	s_cbranch_scc1 .LmlaO_skipdma
	ds_read_b128 v[32:35], v168 offset:20480
	ds_read_b128 v[40:43], v170 offset:20480
	ds_read_b128 v[44:47], v172 offset:20480
	ds_read_b128 v[88:91], v174 offset:20480
	ds_read_b128 v[92:95], v176 offset:20480
	ds_read_b128 v[96:99], v244 offset:20480
	ds_read_b128 v[36:39], v168 offset:26624
	ds_read_b128 v[148:151], v170 offset:26624
	ds_read_b128 v[152:155], v172 offset:26624
	ds_read_b128 v[156:159], v174 offset:26624
	ds_read_b128 v[208:211], v176 offset:26624
	ds_read_b128 v[212:215], v244 offset:26624
	s_add_u32 m0, s21, s32
	s_add_u32 s18, s21, s73
	global_load_lds_dwordx4 v120, s[36:37]
	s_add_u32 m0, m0, 0x400
	s_nop 0
	global_load_lds_dwordx4 v122, s[36:37]
	s_add_u32 m0, m0, 0x400
	s_nop 0
	global_load_lds_dwordx4 v124, s[36:37]
	s_add_u32 m0, s18, 0x3000
	s_nop 0
	global_load_lds_dwordx4 v116, s[38:39]
	s_add_u32 m0, s18, 0x3400
	s_nop 0
	global_load_lds_dwordx4 v118, s[38:39]
	s_waitcnt lgkmcnt(11)
	v_mfma_f32_32x32x16_bf16 v[48:63], v[32:35], v[84:87], v[228:243]
	ds_read_b128 v[216:219], v245 offset:32768
	ds_read_b128 v[108:111], v246 offset:32768
	s_waitcnt lgkmcnt(12)
	v_mfma_f32_32x32x16_bf16 v[48:63], v[40:43], v[80:83], v[48:63]
	s_waitcnt lgkmcnt(11)
	v_mfma_f32_32x32x16_bf16 v[48:63], v[44:47], v[76:79], v[48:63]
	s_waitcnt lgkmcnt(10)
	v_mfma_f32_32x32x16_bf16 v[48:63], v[88:91], v[72:75], v[48:63]
	ds_read_b128 v[88:91], v247 offset:32768
	s_waitcnt lgkmcnt(10)
	v_mfma_f32_32x32x16_bf16 v[48:63], v[92:95], v[68:71], v[48:63]
	s_waitcnt lgkmcnt(9)
	v_mfma_f32_32x32x16_bf16 v[48:63], v[96:99], v[64:67], v[48:63]
	ds_read_b128 v[92:95], v248 offset:32768
	ds_read_b128 v[220:223], v245 offset:36864
	ds_read_b128 v[104:107], v246 offset:36864
	ds_read_b128 v[100:103], v247 offset:36864
	ds_read_b128 v[96:99], v248 offset:36864
	s_nop 6
	s_nop 0
	v_exp_f32_e32 v32, v62
	v_exp_f32_e32 v33, v63
	s_nop 0
	v_add_f32_e32 v224, 0, v32
	v_add_f32_e32 v225, 0, v33
	v_cvt_pk_bf16_f32 v63, v32, v33
	s_waitcnt lgkmcnt(13)
	v_mfma_f32_32x32x16_bf16 v[32:47], v[36:39], v[84:87], v[228:243]
	s_waitcnt lgkmcnt(12)
	v_mfma_f32_32x32x16_bf16 v[32:47], v[148:151], v[80:83], v[32:47]
	v_exp_f32_e32 v60, v60
	v_exp_f32_e32 v61, v61
	s_nop 0
	v_add_f32_e32 v224, v60, v224
	v_add_f32_e32 v225, v61, v225
	v_cvt_pk_bf16_f32 v62, v60, v61
	v_exp_f32_e32 v58, v58
	v_exp_f32_e32 v59, v59
	v_exp_f32_e32 v56, v56
	v_exp_f32_e32 v57, v57
	s_waitcnt lgkmcnt(11)
	v_mfma_f32_32x32x16_bf16 v[32:47], v[152:155], v[76:79], v[32:47]
	v_add_f32_e64 v148, v58, v224
	v_add_f32_e64 v149, v59, v225
	v_cvt_pk_bf16_f32 v61, v58, v59
	v_add_f32_e64 v58, v56, v148
	v_add_f32_e64 v59, v57, v149
	v_cvt_pk_bf16_f32 v60, v56, v57
	s_waitcnt lgkmcnt(10)
	v_mfma_f32_32x32x16_bf16 v[32:47], v[156:159], v[72:75], v[32:47]
	v_exp_f32_e32 v54, v54
	v_exp_f32_e32 v55, v55
	s_nop 0
	v_add_f32_e32 v56, v54, v58
	v_add_f32_e32 v57, v55, v59
	v_cvt_pk_bf16_f32 v55, v54, v55
	s_waitcnt lgkmcnt(9)
	v_mfma_f32_32x32x16_bf16 v[32:47], v[208:211], v[68:71], v[32:47]
	v_exp_f32_e32 v52, v52
	v_exp_f32_e32 v53, v53
	s_nop 0
	v_add_f32_e32 v56, v52, v56
	v_add_f32_e32 v57, v53, v57
	v_cvt_pk_bf16_f32 v54, v52, v53
	v_exp_f32_e32 v50, v50
	v_exp_f32_e32 v51, v51
	v_exp_f32_e32 v48, v48
	v_exp_f32_e32 v49, v49
	s_waitcnt lgkmcnt(8)
	v_mfma_f32_32x32x16_bf16 v[32:47], v[212:215], v[64:67], v[32:47]
	v_add_f32_e64 v56, v50, v56
	v_add_f32_e64 v57, v51, v57
	v_cvt_pk_bf16_f32 v53, v50, v51
	v_cvt_pk_bf16_f32 v52, v48, v49
	v_add_f32_e64 v48, v48, v56
	v_add_f32_e64 v49, v49, v57
	s_waitcnt lgkmcnt(0)
	v_mfma_f32_32x32x16_bf16 v[0:15], v[216:219], v[52:55], v[0:15]
	s_nop 3
	v_exp_f32_e32 v46, v46
	v_exp_f32_e32 v47, v47
	v_exp_f32_e32 v44, v44
	v_exp_f32_e32 v45, v45
	v_add_f32_e32 v48, v48, v46
	v_add_f32_e32 v49, v49, v47
	v_cvt_pk_bf16_f32 v47, v46, v47
	v_add_f32_e32 v48, v44, v48
	v_add_f32_e32 v49, v45, v49
	v_cvt_pk_bf16_f32 v46, v44, v45
	v_mfma_f32_32x32x16_bf16 v[16:31], v[220:223], v[52:55], v[16:31]
	v_exp_f32_e32 v42, v42
	v_exp_f32_e32 v43, v43
	v_exp_f32_e32 v40, v40
	v_exp_f32_e32 v41, v41
	v_add_f32_e32 v48, v42, v48
	v_add_f32_e32 v49, v43, v49
	v_cvt_pk_bf16_f32 v45, v42, v43
	v_add_f32_e32 v42, v40, v48
	v_add_f32_e32 v43, v41, v49
	v_cvt_pk_bf16_f32 v44, v40, v41
	v_mfma_f32_32x32x16_bf16 v[0:15], v[108:111], v[60:63], v[0:15]
	v_exp_f32_e32 v38, v38
	v_exp_f32_e32 v39, v39
	v_exp_f32_e32 v36, v36
	v_exp_f32_e32 v37, v37
	v_add_f32_e32 v40, v38, v42
	v_add_f32_e32 v41, v39, v43
	v_cvt_pk_bf16_f32 v39, v38, v39
	v_add_f32_e32 v40, v36, v40
	v_add_f32_e32 v41, v37, v41
	v_cvt_pk_bf16_f32 v38, v36, v37
	v_mfma_f32_32x32x16_bf16 v[16:31], v[104:107], v[60:63], v[16:31]
	v_exp_f32_e32 v34, v34
	v_exp_f32_e32 v35, v35
	v_exp_f32_e32 v32, v32
	v_exp_f32_e32 v33, v33
	v_cvt_pk_bf16_f32 v37, v34, v35
	v_cvt_pk_bf16_f32 v36, v32, v33
	s_nop 1
	v_mfma_f32_32x32x16_bf16 v[0:15], v[88:91], v[36:39], v[0:15]
	v_add_f32_e64 v34, v34, v40
	v_add_f32_e64 v35, v35, v41
	v_add_f32_e64 v32, v32, v34
	v_add_f32_e64 v33, v33, v35
	v_add_f32_e32 v32, v32, v33
	v_add_f32_e32 v126, v126, v32
	v_mfma_f32_32x32x16_bf16 v[16:31], v[100:103], v[36:39], v[16:31]
	v_mfma_f32_32x32x16_bf16 v[0:15], v[92:95], v[44:47], v[0:15]
	v_mfma_f32_32x32x16_bf16 v[16:31], v[96:99], v[44:47], v[16:31]
	s_branch .LBB0_86

; template <int DQK, bool MIXA, bool PIPE>
; DI void attn_item(const Params& P, int layer, char* smem, int b, int h, int qt) {
;     ...
;   auto issue_loads = [&](int kt) __attribute__((always_inline)) {
;     const char* kbp = (const char*)(Kp + (size_t)(kt * 64) * ldk);
;     const char* vbp = (const char*)(VT + kt * 64);
;     char* sk = smem + (kt & 1) * STG_B;
; #pragma unroll
;     for (int i = 0; i < NKI; ++i)
;       __builtin_amdgcn_global_load_lds((const unsigned*)(kbp + koff[i]), (unsigned*)(sk + (w * NKI + i) * 1024), 16, 0, 0);
; #pragma unroll
;     for (int i = 0; i < 2; ++i)
;       __builtin_amdgcn_global_load_lds((const unsigned*)(vbp + voff[i]), (unsigned*)(sk + KTILE_B + (w * 2 + i) * 1024), 16, 0, 0);
;     if (MIXA) {
;       if (kt <= cw) {
;         const unsigned* mp = mask + mask_base(b, cw) + (2 * kt) * 64 + (qpos & 63);
;         mwn[0] = mp[0]; mwn[1] = mp[64];
;       }
;     }
;     ...
;       bf16x8 kf[2][NS];
; #pragma unroll
;       for (int kb = 0; kb < 2; ++kb)
; #pragma unroll
;         for (int s = 0; s < NS; ++s) kf[kb][s] = *(const bf16x8*)(Ks + (32 * kb + pr) * KROWB + (((2 * s + H) ^ swk) << 4));
;       __builtin_amdgcn_sched_barrier(0);
;       f32x16 sacc[2];
; #pragma unroll
;       for (int kb = 0; kb < 2; ++kb)
; #pragma unroll
;         for (int i = 0; i < 16; ++i) sacc[kb][i] = 0.f;
; #pragma unroll
;       for (int s = 0; s < NS; ++s) sacc[0] = __builtin_amdgcn_mfma_f32_32x32x16_bf16(kf[0][s], qf[s], sacc[0], 0, 0, 0);
;       bf16x8 vf[2][2][2];
; #pragma unroll
;       for (int d = 0; d < 2; ++d)
; #pragma unroll
;         for (int kb = 0; kb < 2; ++kb)
; #pragma unroll
;           for (int s2 = 0; s2 < 2; ++s2)
;             vf[d][kb][s2] = *(const bf16x8*)(Vs + (d * 32 + l31) * 128 + (((4 * kb + 2 * s2 + H) ^ swv) << 4));
;       __builtin_amdgcn_sched_barrier(0);
;       const bool near = MIXA && (kc >= cw - 2);
.LBB0_110:
	s_add_i32 s20, s22, 1
	s_movk_i32 s21, 0x5000
	s_cmp_gt_i32 s22, s78
	s_cbranch_scc1 .LmixE_skipdma
	ds_read_b128 v[36:39], v168
	ds_read_b128 v[40:43], v170
	ds_read_b128 v[44:47], v172
	ds_read_b128 v[80:83], v174
	ds_read_b128 v[32:35], v168 offset:4096
	ds_read_b128 v[120:123], v170 offset:4096
	ds_read_b128 v[116:119], v172 offset:4096
	ds_read_b128 v[108:111], v174 offset:4096
	s_add_u32 m0, s21, s32
	s_nop 0
	global_load_lds_dwordx4 v140, s[36:37]
	s_add_u32 m0, m0, 0x400
	s_nop 0
	global_load_lds_dwordx4 v142, s[36:37]
	s_add_u32 m0, m0, 0x1c00
	s_nop 0
	global_load_lds_dwordx4 v132, s[38:39]
	s_add_u32 m0, m0, 0x400
	s_nop 0
	global_load_lds_dwordx4 v134, s[38:39]
	s_cmp_lt_i32 s22, s78
	s_cselect_b64 s[42:43], exec, 0
	s_cbranch_scc0 .LmixE_m112
	global_load_dword v156, v130, s[76:77] offset:512
	global_load_dword v136, v130, s[76:77] offset:768
.LmixE_m112:
	s_waitcnt lgkmcnt(7)
	v_mfma_f32_32x32x16_bf16 v[48:63], v[36:39], v[76:79], v[228:243]
	ds_read_b128 v[112:115], v245 offset:8192
	ds_read_b128 v[100:103], v246 offset:8192
	s_waitcnt lgkmcnt(8)
	v_mfma_f32_32x32x16_bf16 v[48:63], v[40:43], v[72:75], v[48:63]
	s_waitcnt lgkmcnt(7)
	v_mfma_f32_32x32x16_bf16 v[48:63], v[44:47], v[68:71], v[48:63]
	s_waitcnt lgkmcnt(6)
	v_mfma_f32_32x32x16_bf16 v[48:63], v[80:83], v[64:67], v[48:63]
	ds_read_b128 v[80:83], v247 offset:8192
	ds_read_b128 v[84:87], v248 offset:8192
	ds_read_b128 v[104:107], v245 offset:12288
	ds_read_b128 v[96:99], v246 offset:12288
	ds_read_b128 v[92:95], v247 offset:12288
	ds_read_b128 v[88:91], v248 offset:12288
	s_nop 4
	s_cmp_ge_i32 s22, s93
	s_cbranch_scc1 .Lmixa_near_0

; DI unsigned pk2(float a, float b) { f32x2 v = {a, b}; return __builtin_bit_cast(unsigned, __builtin_convertvector(v, bf16x2)); }
; template <int DQK, bool MIXA, bool PIPE>
; DI void attn_item(const Params& P, int layer, char* smem, int b, int h, int qt) {
;     ...
;       auto chunk = [&](int kb, int c) __attribute__((always_inline)) {
;         const int s2 = 1 - (c >> 2), e = 3 - (c & 3);
;         const int r0 = 8 * s2 + 2 * e;
;         if (MIXA && c == 4) mrot[kb] <<= 8;
;         f32x2 xv2 = {sacc[kb][r0], sacc[kb][r0 + 1]};
;         xv2 = xv2 * sl2v - mfixv;
;         if (MIXA) {
;           if (near) {
;             const int kl = 16 * (r0 >> 3) + 8 * H + (r0 & 7);
;             const int rel = kc * 64 + 32 * kb + kl - qpos;
;             xv2.x += biasT[rel + 192];
;             xv2.y += biasT[rel + 193];
;           }
;         }
;         f32x2 p2 = {__builtin_amdgcn_exp2f(xv2.x), __builtin_amdgcn_exp2f(xv2.y)};
;         if (MIXA) {
;           float px = p2.x, py = p2.y;
;           asm volatile("v_add_co_u32 %0, vcc, %0, %0\n\tv_cndmask_b32 %1, 0, %1, vcc" : "+v"(mrot[kb]), "+v"(py) : : "vcc");
;           asm volatile("v_add_co_u32 %0, vcc, %0, %0\n\tv_cndmask_b32 %1, 0, %1, vcc" : "+v"(mrot[kb]), "+v"(px) : : "vcc");
;           p2.x = px; p2.y = py;
;         }
;         ls2 += p2;
;         pkw[kb][s2][e] = pk2(p2.x, p2.y);
;       };
;       {
;         int c0 = 0;
; #pragma unroll
;         for (int s = 0; s < NS; ++s) {
;           sacc[1] = __builtin_amdgcn_mfma_f32_32x32x16_bf16(kf[1][s], qf[s], sacc[1], 0, 0, 0);
;           const int cend = (8 * (s + 1)) / NS;
; #pragma unroll
;           for (int c = 0; c < 8; ++c) if (c >= c0 && c < cend) chunk(0, c);
;           c0 = cend;
;           __builtin_amdgcn_sched_barrier(0);
;         }
.Lmixa_back_1:
	v_exp_f32_e32 v61, v61
	v_exp_f32_e32 v60, v60
	s_waitcnt lgkmcnt(11)
	v_mfma_f32_32x32x16_bf16 v[32:47], v[32:35], v[76:79], v[228:243]
	v_add_co_u32 v166, vcc, v166, v166
	v_cndmask_b32 v61, 0, v61, vcc
	s_nop 0
	v_add_co_u32 v166, vcc, v166, v166
	v_cndmask_b32 v60, 0, v60, vcc
	s_cbranch_scc1 .Lmixa_near_2

; DI unsigned pk2(float a, float b) { f32x2 v = {a, b}; return __builtin_bit_cast(unsigned, __builtin_convertvector(v, bf16x2)); }
; template <int DQK, bool MIXA, bool PIPE>
; DI void attn_item(const Params& P, int layer, char* smem, int b, int h, int qt) {
;     ...
;       auto chunk = [&](int kb, int c) __attribute__((always_inline)) {
;         const int s2 = 1 - (c >> 2), e = 3 - (c & 3);
;         const int r0 = 8 * s2 + 2 * e;
;         if (MIXA && c == 4) mrot[kb] <<= 8;
;         f32x2 xv2 = {sacc[kb][r0], sacc[kb][r0 + 1]};
;         xv2 = xv2 * sl2v - mfixv;
;         if (MIXA) {
;           if (near) {
;             const int kl = 16 * (r0 >> 3) + 8 * H + (r0 & 7);
;             const int rel = kc * 64 + 32 * kb + kl - qpos;
;             xv2.x += biasT[rel + 192];
;             xv2.y += biasT[rel + 193];
;           }
;         }
;         f32x2 p2 = {__builtin_amdgcn_exp2f(xv2.x), __builtin_amdgcn_exp2f(xv2.y)};
;         if (MIXA) {
;           float px = p2.x, py = p2.y;
;           asm volatile("v_add_co_u32 %0, vcc, %0, %0\n\tv_cndmask_b32 %1, 0, %1, vcc" : "+v"(mrot[kb]), "+v"(py) : : "vcc");
;           asm volatile("v_add_co_u32 %0, vcc, %0, %0\n\tv_cndmask_b32 %1, 0, %1, vcc" : "+v"(mrot[kb]), "+v"(px) : : "vcc");
;           p2.x = px; p2.y = py;
;         }
;         ls2 += p2;
;         pkw[kb][s2][e] = pk2(p2.x, p2.y);
;       };
;       {
;         int c0 = 0;
; #pragma unroll
;         for (int s = 0; s < NS; ++s) {
;           sacc[1] = __builtin_amdgcn_mfma_f32_32x32x16_bf16(kf[1][s], qf[s], sacc[1], 0, 0, 0);
;           const int cend = (8 * (s + 1)) / NS;
; #pragma unroll
;           for (int c = 0; c < 8; ++c) if (c >= c0 && c < cend) chunk(0, c);
;           c0 = cend;
;           __builtin_amdgcn_sched_barrier(0);
;         }
.Lmixa_back_3:
	s_waitcnt lgkmcnt(10)
	v_mfma_f32_32x32x16_bf16 v[32:47], v[120:123], v[72:75], v[32:47]
	v_exp_f32_e32 v57, v57
	v_exp_f32_e32 v56, v56
	v_add_co_u32 v166, vcc, v166, v166
	v_cndmask_b32 v57, 0, v57, vcc
	s_nop 0
	v_add_co_u32 v166, vcc, v166, v166
	v_cndmask_b32 v56, 0, v56, vcc
	s_cbranch_scc1 .Lmixa_near_4

; DI unsigned pk2(float a, float b) { f32x2 v = {a, b}; return __builtin_bit_cast(unsigned, __builtin_convertvector(v, bf16x2)); }
; template <int DQK, bool MIXA, bool PIPE>
; DI void attn_item(const Params& P, int layer, char* smem, int b, int h, int qt) {
;     ...
;       auto chunk = [&](int kb, int c) __attribute__((always_inline)) {
;         const int s2 = 1 - (c >> 2), e = 3 - (c & 3);
;         const int r0 = 8 * s2 + 2 * e;
;         if (MIXA && c == 4) mrot[kb] <<= 8;
;         f32x2 xv2 = {sacc[kb][r0], sacc[kb][r0 + 1]};
;         xv2 = xv2 * sl2v - mfixv;
;         if (MIXA) {
;           if (near) {
;             const int kl = 16 * (r0 >> 3) + 8 * H + (r0 & 7);
;             const int rel = kc * 64 + 32 * kb + kl - qpos;
;             xv2.x += biasT[rel + 192];
;             xv2.y += biasT[rel + 193];
;           }
;         }
;         f32x2 p2 = {__builtin_amdgcn_exp2f(xv2.x), __builtin_amdgcn_exp2f(xv2.y)};
;         if (MIXA) {
;           float px = p2.x, py = p2.y;
;           asm volatile("v_add_co_u32 %0, vcc, %0, %0\n\tv_cndmask_b32 %1, 0, %1, vcc" : "+v"(mrot[kb]), "+v"(py) : : "vcc");
;           asm volatile("v_add_co_u32 %0, vcc, %0, %0\n\tv_cndmask_b32 %1, 0, %1, vcc" : "+v"(mrot[kb]), "+v"(px) : : "vcc");
;           p2.x = px; p2.y = py;
;         }
;         ls2 += p2;
;         pkw[kb][s2][e] = pk2(p2.x, p2.y);
;       };
;       {
;         int c0 = 0;
; #pragma unroll
;         for (int s = 0; s < NS; ++s) {
;           sacc[1] = __builtin_amdgcn_mfma_f32_32x32x16_bf16(kf[1][s], qf[s], sacc[1], 0, 0, 0);
;           const int cend = (8 * (s + 1)) / NS;
; #pragma unroll
;           for (int c = 0; c < 8; ++c) if (c >= c0 && c < cend) chunk(0, c);
;           c0 = cend;
;           __builtin_amdgcn_sched_barrier(0);
;         }
.Lmixa_back_5:
	s_waitcnt lgkmcnt(9)
	v_mfma_f32_32x32x16_bf16 v[32:47], v[116:119], v[68:71], v[32:47]
	v_exp_f32_e32 v53, v53
	v_exp_f32_e32 v52, v52
	v_add_co_u32 v120, vcc, v120, v120
	v_cndmask_b32 v53, 0, v53, vcc
	s_nop 0
	v_add_co_u32 v120, vcc, v120, v120
	v_cndmask_b32 v52, 0, v52, vcc
	s_cbranch_scc1 .Lmixa_near_6

; DI unsigned pk2(float a, float b) { f32x2 v = {a, b}; return __builtin_bit_cast(unsigned, __builtin_convertvector(v, bf16x2)); }
; template <int DQK, bool MIXA, bool PIPE>
; DI void attn_item(const Params& P, int layer, char* smem, int b, int h, int qt) {
;     ...
;       auto chunk = [&](int kb, int c) __attribute__((always_inline)) {
;         const int s2 = 1 - (c >> 2), e = 3 - (c & 3);
;         const int r0 = 8 * s2 + 2 * e;
;         if (MIXA && c == 4) mrot[kb] <<= 8;
;         f32x2 xv2 = {sacc[kb][r0], sacc[kb][r0 + 1]};
;         xv2 = xv2 * sl2v - mfixv;
;         if (MIXA) {
;           if (near) {
;             const int kl = 16 * (r0 >> 3) + 8 * H + (r0 & 7);
;             const int rel = kc * 64 + 32 * kb + kl - qpos;
;             xv2.x += biasT[rel + 192];
;             xv2.y += biasT[rel + 193];
;           }
;         }
;         f32x2 p2 = {__builtin_amdgcn_exp2f(xv2.x), __builtin_amdgcn_exp2f(xv2.y)};
;         if (MIXA) {
;           float px = p2.x, py = p2.y;
;           asm volatile("v_add_co_u32 %0, vcc, %0, %0\n\tv_cndmask_b32 %1, 0, %1, vcc" : "+v"(mrot[kb]), "+v"(py) : : "vcc");
;           asm volatile("v_add_co_u32 %0, vcc, %0, %0\n\tv_cndmask_b32 %1, 0, %1, vcc" : "+v"(mrot[kb]), "+v"(px) : : "vcc");
;           p2.x = px; p2.y = py;
;         }
;         ls2 += p2;
;         pkw[kb][s2][e] = pk2(p2.x, p2.y);
;       };
;       {
;         int c0 = 0;
; #pragma unroll
;         for (int s = 0; s < NS; ++s) {
;           sacc[1] = __builtin_amdgcn_mfma_f32_32x32x16_bf16(kf[1][s], qf[s], sacc[1], 0, 0, 0);
;           const int cend = (8 * (s + 1)) / NS;
; #pragma unroll
;           for (int c = 0; c < 8; ++c) if (c >= c0 && c < cend) chunk(0, c);
;           c0 = cend;
;           __builtin_amdgcn_sched_barrier(0);
;         }
;       }
;       bf16x8 pf0[2], pf1[2];
; #pragma unroll
;       for (int s2 = 0; s2 < 2; ++s2) { u32x4 t = {pkw[0][s2][0], pkw[0][s2][1], pkw[0][s2][2], pkw[0][s2][3]}; pf0[s2] = __builtin_bit_cast(bf16x8, t); }
; #pragma unroll
;       for (int j = 0; j < 4; ++j) {
;         const int s2 = j >> 1, d = j & 1;
;         o[d] = __builtin_amdgcn_mfma_f32_32x32x16_bf16(vf[d][0][s2], pf0[s2], o[d], 0, 0, 0);
.Lmixa_back_7:
	s_waitcnt lgkmcnt(8)
	v_mfma_f32_32x32x16_bf16 v[32:47], v[108:111], v[64:67], v[32:47]
	v_exp_f32_e32 v119, v49
	v_exp_f32_e32 v118, v48
	v_add_co_u32 v120, vcc, v120, v120
	v_cndmask_b32 v119, 0, v119, vcc
	v_cvt_pk_bf16_f32 v49, v116, v117
	v_cvt_pk_bf16_f32 v50, v52, v53
	v_cvt_pk_bf16_f32 v51, v54, v55
	v_add_co_u32 v120, vcc, v120, v120
	v_cndmask_b32 v118, 0, v118, vcc
	s_nop 0
	v_cvt_pk_bf16_f32 v48, v118, v119
	s_waitcnt lgkmcnt(0)
	s_nop 0
	v_mfma_f32_32x32x16_bf16 v[0:15], v[112:115], v[48:51], v[0:15]
	s_nop 1
	s_cbranch_scc1 .Lmixa_near_8

; template <int DQK, bool MIXA, bool PIPE>
; DI void attn_item(const Params& P, int layer, char* smem, int b, int h, int qt) {
;     ...
;   auto issue_loads = [&](int kt) __attribute__((always_inline)) {
;     const char* kbp = (const char*)(Kp + (size_t)(kt * 64) * ldk);
;     const char* vbp = (const char*)(VT + kt * 64);
;     char* sk = smem + (kt & 1) * STG_B;
; #pragma unroll
;     for (int i = 0; i < NKI; ++i)
;       __builtin_amdgcn_global_load_lds((const unsigned*)(kbp + koff[i]), (unsigned*)(sk + (w * NKI + i) * 1024), 16, 0, 0);
; #pragma unroll
;     for (int i = 0; i < 2; ++i)
;       __builtin_amdgcn_global_load_lds((const unsigned*)(vbp + voff[i]), (unsigned*)(sk + KTILE_B + (w * 2 + i) * 1024), 16, 0, 0);
;     if (MIXA) {
;       if (kt <= cw) {
;         const unsigned* mp = mask + mask_base(b, cw) + (2 * kt) * 64 + (qpos & 63);
;         mwn[0] = mp[0]; mwn[1] = mp[64];
;       }
;     }
;     ...
;       bf16x8 kf[2][NS];
; #pragma unroll
;       for (int kb = 0; kb < 2; ++kb)
; #pragma unroll
;         for (int s = 0; s < NS; ++s) kf[kb][s] = *(const bf16x8*)(Ks + (32 * kb + pr) * KROWB + (((2 * s + H) ^ swk) << 4));
;       __builtin_amdgcn_sched_barrier(0);
;       f32x16 sacc[2];
; #pragma unroll
;       for (int kb = 0; kb < 2; ++kb)
; #pragma unroll
;         for (int i = 0; i < 16; ++i) sacc[kb][i] = 0.f;
; #pragma unroll
;       for (int s = 0; s < NS; ++s) sacc[0] = __builtin_amdgcn_mfma_f32_32x32x16_bf16(kf[0][s], qf[s], sacc[0], 0, 0, 0);
;       bf16x8 vf[2][2][2];
; #pragma unroll
;       for (int d = 0; d < 2; ++d)
; #pragma unroll
;         for (int kb = 0; kb < 2; ++kb)
; #pragma unroll
;           for (int s2 = 0; s2 < 2; ++s2)
;             vf[d][kb][s2] = *(const bf16x8*)(Vs + (d * 32 + l31) * 128 + (((4 * kb + 2 * s2 + H) ^ swv) << 4));
;       __builtin_amdgcn_sched_barrier(0);
;       const bool near = MIXA && (kc >= cw - 2);
.Lmixa_o_o110:
	s_add_i32 s20, s22, 1
	s_mov_b32 s21, 0
	s_cmp_gt_i32 s22, s78
	s_cbranch_scc1 .LmixO_skipdma
	ds_read_b128 v[36:39], v168 offset:20480
	ds_read_b128 v[40:43], v170 offset:20480
	ds_read_b128 v[44:47], v172 offset:20480
	ds_read_b128 v[80:83], v174 offset:20480
	ds_read_b128 v[32:35], v168 offset:24576
	ds_read_b128 v[120:123], v170 offset:24576
	ds_read_b128 v[116:119], v172 offset:24576
	ds_read_b128 v[108:111], v174 offset:24576
	s_add_u32 m0, s21, s32
	s_nop 0
	global_load_lds_dwordx4 v140, s[36:37]
	s_add_u32 m0, m0, 0x400
	s_nop 0
	global_load_lds_dwordx4 v142, s[36:37]
	s_add_u32 m0, m0, 0x1c00
	s_nop 0
	global_load_lds_dwordx4 v132, s[38:39]
	s_add_u32 m0, m0, 0x400
	s_nop 0
	global_load_lds_dwordx4 v134, s[38:39]
	s_cmp_lt_i32 s22, s78
	s_cselect_b64 s[42:43], exec, 0
	s_cbranch_scc0 .LmixO_m112
	global_load_dword v156, v130, s[76:77] offset:512
	global_load_dword v136, v130, s[76:77] offset:768
.LmixO_m112:
	s_waitcnt lgkmcnt(7)
	v_mfma_f32_32x32x16_bf16 v[48:63], v[36:39], v[76:79], v[228:243]
	ds_read_b128 v[112:115], v245 offset:28672
	ds_read_b128 v[100:103], v246 offset:28672
	s_waitcnt lgkmcnt(8)
	v_mfma_f32_32x32x16_bf16 v[48:63], v[40:43], v[72:75], v[48:63]
	s_waitcnt lgkmcnt(7)
	v_mfma_f32_32x32x16_bf16 v[48:63], v[44:47], v[68:71], v[48:63]
	s_waitcnt lgkmcnt(6)
	v_mfma_f32_32x32x16_bf16 v[48:63], v[80:83], v[64:67], v[48:63]
	ds_read_b128 v[80:83], v247 offset:28672
	ds_read_b128 v[84:87], v248 offset:28672
	ds_read_b128 v[104:107], v245 offset:32768
	ds_read_b128 v[96:99], v246 offset:32768
	ds_read_b128 v[92:95], v247 offset:32768
	ds_read_b128 v[88:91], v248 offset:32768
	s_nop 4
	s_cmp_ge_i32 s22, s93
	s_cbranch_scc1 .Lmixa_o_near_0
